# MLA attention loop: next tile's LDS-DMA issue moved from the loop top into the VALU-only part of the tile body
# speedup vs baseline: 1.1096x; 1.0046x over previous
.LBB0_381:
	s_waitcnt lgkmcnt(0)
	s_barrier
.LBB0_383:
	s_and_b32 s2, s27, 3
	v_lshl_or_b32 v107, s2, 14, v103
	v_add_u32_e32 v36, v107, v115
	v_add_u32_e32 v37, v107, v116
	v_add_u32_e32 v38, v107, v117
	v_add_u32_e32 v39, v107, v118
	v_add_u32_e32 v40, v107, v119
	v_add_u32_e32 v41, v107, v120
	ds_read_b128 v[132:135], v36
	ds_read_b128 v[136:139], v37
	ds_read_b128 v[140:143], v38
	ds_read_b128 v[144:147], v39
	ds_read_b128 v[148:151], v40
	ds_read_b128 v[152:155], v41
	ds_read_b128 v[156:159], v36 offset:8192
	ds_read_b128 v[160:163], v37 offset:8192
	ds_read_b128 v[164:167], v38 offset:8192
	ds_read_b128 v[168:171], v39 offset:8192
	ds_read_b128 v[172:175], v40 offset:8192
	ds_read_b128 v[176:179], v41 offset:8192
	v_lshl_add_u32 v114, s2, 13, v129
	s_waitcnt lgkmcnt(11)
	v_mfma_f32_32x32x16_bf16 v[52:67], v[132:135], v[68:71], 0
	s_waitcnt lgkmcnt(10)
	v_mfma_f32_32x32x16_bf16 v[52:67], v[136:139], v[72:75], v[52:67]
	s_waitcnt lgkmcnt(9)
	v_mfma_f32_32x32x16_bf16 v[52:67], v[140:143], v[76:79], v[52:67]
	s_waitcnt lgkmcnt(8)
	v_mfma_f32_32x32x16_bf16 v[52:67], v[144:147], v[80:83], v[52:67]
	s_waitcnt lgkmcnt(7)
	v_mfma_f32_32x32x16_bf16 v[52:67], v[148:151], v[84:87], v[52:67]
	s_waitcnt lgkmcnt(6)
	v_mfma_f32_32x32x16_bf16 v[52:67], v[152:155], v[88:91], v[52:67]
	s_waitcnt lgkmcnt(0)
	v_mfma_f32_32x32x16_bf16 v[36:51], v[156:159], v[68:71], 0
	v_add_u32_e32 v148, v114, v121
	v_add_u32_e32 v149, v114, v122
	ds_read_b64 v[132:133], v148
	ds_read_b64 v[134:135], v149
	v_mfma_f32_32x32x16_bf16 v[36:51], v[160:163], v[72:75], v[36:51]
	v_add_u32_e32 v150, v114, v123
	v_add_u32_e32 v151, v114, v124
	ds_read_b64 v[136:137], v150
	ds_read_b64 v[138:139], v151
	v_mfma_f32_32x32x16_bf16 v[36:51], v[164:167], v[76:79], v[36:51]
	v_add_u32_e32 v152, v114, v125
	v_add_u32_e32 v153, v114, v126
	ds_read_b64 v[140:141], v152
	ds_read_b64 v[142:143], v153
	v_mfma_f32_32x32x16_bf16 v[36:51], v[168:171], v[80:83], v[36:51]
	v_add_u32_e32 v154, v114, v127
	v_add_u32_e32 v155, v114, v128
	ds_read_b64 v[144:145], v154
	ds_read_b64 v[146:147], v155
	v_mfma_f32_32x32x16_bf16 v[36:51], v[172:175], v[84:87], v[36:51]
	v_mfma_f32_32x32x16_bf16 v[36:51], v[176:179], v[88:91], v[36:51]
	ds_read_b64 v[156:157], v152 offset:4096
	ds_read_b64 v[158:159], v153 offset:4096
	ds_read_b64 v[160:161], v154 offset:4096
	ds_read_b64 v[162:163], v155 offset:4096
	ds_read_b64 v[152:153], v150 offset:4096
	ds_read_b64 v[154:155], v151 offset:4096
	ds_read_b64 v[148:149], v148 offset:4096
	ds_read_b64 v[150:151], v149 offset:4096
	v_max3_f32 v107, v52, v53, v54
	v_max3_f32 v107, v107, v55, v56
	v_max3_f32 v107, v107, v57, v58
	v_max3_f32 v107, v107, v59, v60
	v_max3_f32 v107, v107, v61, v62
	v_max3_f32 v107, v107, v63, v64
	v_max3_f32 v107, v107, v65, v66
	v_max_f32_e32 v107, v107, v67
	v_max3_f32 v114, v36, v37, v38
	v_max3_f32 v114, v114, v39, v40
	v_max3_f32 v114, v114, v41, v42
	v_max3_f32 v114, v114, v43, v44
	v_max3_f32 v114, v114, v45, v46
	v_max3_f32 v114, v114, v47, v48
	v_max3_f32 v114, v114, v49, v50
	v_max3_f32 v107, v107, v114, v51
	v_mul_f32_e32 v107, s33, v107
	v_mov_b32_e32 v172, v107
	s_nop 1
	v_permlane32_swap_b32 v107, v172
	s_nop 1
	v_max3_f32 v107, v131, v107, v172
	v_sub_f32_e32 v114, v131, v107
	v_exp_f32_e32 v114, v114
	v_cmp_neq_f32_e32 vcc, v107, v131
	s_cbranch_vccz .Lat96_keep
	v_pk_mul_f32 v[34:35], v[34:35], v[114:115] op_sel_hi:[1,0]
	v_pk_mul_f32 v[32:33], v[32:33], v[114:115] op_sel_hi:[1,0]
	v_pk_mul_f32 v[30:31], v[30:31], v[114:115] op_sel_hi:[1,0]
	v_pk_mul_f32 v[28:29], v[28:29], v[114:115] op_sel_hi:[1,0]
	v_pk_mul_f32 v[26:27], v[26:27], v[114:115] op_sel_hi:[1,0]
	v_pk_mul_f32 v[24:25], v[24:25], v[114:115] op_sel_hi:[1,0]
	v_pk_mul_f32 v[22:23], v[22:23], v[114:115] op_sel_hi:[1,0]
	v_pk_mul_f32 v[20:21], v[20:21], v[114:115] op_sel_hi:[1,0]
	v_pk_mul_f32 v[18:19], v[18:19], v[114:115] op_sel_hi:[1,0]
	v_pk_mul_f32 v[16:17], v[16:17], v[114:115] op_sel_hi:[1,0]
	v_pk_mul_f32 v[14:15], v[14:15], v[114:115] op_sel_hi:[1,0]
	v_pk_mul_f32 v[12:13], v[12:13], v[114:115] op_sel_hi:[1,0]
	v_pk_mul_f32 v[10:11], v[10:11], v[114:115] op_sel_hi:[1,0]
	v_pk_mul_f32 v[8:9], v[8:9], v[114:115] op_sel_hi:[1,0]
	v_pk_mul_f32 v[6:7], v[6:7], v[114:115] op_sel_hi:[1,0]
	v_pk_mul_f32 v[4:5], v[4:5], v[114:115] op_sel_hi:[1,0]
.Lat96_keep:
	v_fma_f32 v52, v52, s33, -v107
	v_fma_f32 v53, v53, s33, -v107
	v_fma_f32 v54, v54, s33, -v107
	v_fma_f32 v55, v55, s33, -v107
	v_fma_f32 v56, v56, s33, -v107
	v_fma_f32 v57, v57, s33, -v107
	v_fma_f32 v58, v58, s33, -v107
	v_fma_f32 v59, v59, s33, -v107
	v_exp_f32_e32 v52, v52
	v_exp_f32_e32 v53, v53
	v_exp_f32_e32 v54, v54
	v_exp_f32_e32 v55, v55
	v_exp_f32_e32 v56, v56
	v_exp_f32_e32 v57, v57
	v_exp_f32_e32 v58, v58
	v_exp_f32_e32 v59, v59
	v_cvt_pk_bf16_f32 v164, v52, v53
	v_cvt_pk_bf16_f32 v165, v54, v55
	v_cvt_pk_bf16_f32 v166, v56, v57
	v_cvt_pk_bf16_f32 v167, v58, v59
	v_add_f32_e32 v52, v52, v53
	v_add_f32_e32 v54, v54, v55
	v_add_f32_e32 v56, v56, v57
	v_add_f32_e32 v58, v58, v59
	v_add_f32_e32 v52, v52, v54
	v_add_f32_e32 v56, v56, v58
	v_add_f32_e32 v52, v52, v56
	s_cmp_ge_i32 s27, s5
	s_cbranch_scc1 .Lat96_nodma
	s_cmp_eq_u32 s4, s0
	s_cselect_b64 s[2:3], -1, 0
	s_and_b64 vcc, s[24:25], s[2:3]
	s_and_b32 s2, s4, 3
	v_lshl_add_u32 v53, s2, 14, v99
	v_cndmask_b32_e32 v59, v109, v95, vcc
	v_readfirstlane_b32 s3, v53
	v_add_u32_e32 v53, 0x400, v53
	v_cndmask_b32_e32 v58, v108, v94, vcc
	s_mov_b32 m0, s3
	v_readfirstlane_b32 s3, v53
	v_lshl_add_u32 v53, s2, 13, v101
	v_cndmask_b32_e32 v57, v111, v97, vcc
	v_cndmask_b32_e32 v56, v110, v96, vcc
	global_load_lds_dwordx4 v[58:59], off
	s_mov_b32 m0, s3
	v_readfirstlane_b32 s2, v53
	v_cndmask_b32_e32 v55, v113, v105, vcc
	v_cndmask_b32_e32 v54, v112, v104, vcc
	global_load_lds_dwordx4 v[56:57], off
	s_mov_b32 m0, s2
	v_cndmask_b32_e32 v106, v106, v102, vcc
	global_load_lds_dwordx4 v[54:55], off
	v_cndmask_b32_e32 v2, v2, v100, vcc
	v_lshl_add_u64 v[108:109], v[2:3], 1, v[58:59]
	v_lshlrev_b32_e32 v53, 1, v106
	v_add_co_u32_e32 v110, vcc, v53, v56
	s_nop 1
	v_addc_co_u32_e32 v111, vcc, 0, v57, vcc
	v_lshl_add_u64 v[112:113], v[54:55], 0, s[82:83]
	s_add_i32 s4, s4, 1
.Lat96_nodma:
	v_fma_f32 v60, v60, s33, -v107
	v_fma_f32 v61, v61, s33, -v107
	v_fma_f32 v62, v62, s33, -v107
	v_fma_f32 v63, v63, s33, -v107
	v_fma_f32 v64, v64, s33, -v107
	v_fma_f32 v65, v65, s33, -v107
	v_fma_f32 v66, v66, s33, -v107
	v_fma_f32 v67, v67, s33, -v107
	v_exp_f32_e32 v60, v60
	v_exp_f32_e32 v61, v61
	v_exp_f32_e32 v62, v62
	v_exp_f32_e32 v63, v63
	v_exp_f32_e32 v64, v64
	v_exp_f32_e32 v65, v65
	v_exp_f32_e32 v66, v66
	v_exp_f32_e32 v67, v67
	v_cvt_pk_bf16_f32 v168, v60, v61
	v_cvt_pk_bf16_f32 v169, v62, v63
	v_cvt_pk_bf16_f32 v170, v64, v65
	v_cvt_pk_bf16_f32 v171, v66, v67
	v_add_f32_e32 v60, v60, v61
	v_add_f32_e32 v62, v62, v63
	v_add_f32_e32 v64, v64, v65
	v_add_f32_e32 v66, v66, v67
	v_add_f32_e32 v60, v60, v62
	v_add_f32_e32 v64, v64, v66
	v_add_f32_e32 v60, v60, v64
	s_waitcnt lgkmcnt(0)
	v_mfma_f32_32x32x16_bf16 v[20:35], v[132:135], v[164:167], v[20:35]
	v_fma_f32 v36, v36, s33, -v107
	v_fma_f32 v37, v37, s33, -v107
	v_fma_f32 v38, v38, s33, -v107
	v_fma_f32 v39, v39, s33, -v107
	v_fma_f32 v40, v40, s33, -v107
	v_fma_f32 v41, v41, s33, -v107
	v_fma_f32 v42, v42, s33, -v107
	v_fma_f32 v43, v43, s33, -v107
	v_mfma_f32_32x32x16_bf16 v[4:19], v[148:151], v[164:167], v[4:19]
	v_exp_f32_e32 v36, v36
	v_exp_f32_e32 v37, v37
	v_exp_f32_e32 v38, v38
	v_exp_f32_e32 v39, v39
	v_exp_f32_e32 v40, v40
	v_exp_f32_e32 v41, v41
	v_exp_f32_e32 v42, v42
	v_exp_f32_e32 v43, v43
	v_mfma_f32_32x32x16_bf16 v[20:35], v[136:139], v[168:171], v[20:35]
	v_cvt_pk_bf16_f32 v172, v36, v37
	v_cvt_pk_bf16_f32 v173, v38, v39
	v_cvt_pk_bf16_f32 v174, v40, v41
	v_cvt_pk_bf16_f32 v175, v42, v43
	v_add_f32_e32 v36, v36, v37
	v_add_f32_e32 v38, v38, v39
	v_add_f32_e32 v40, v40, v41
	v_add_f32_e32 v42, v42, v43
	v_add_f32_e32 v36, v36, v38
	v_add_f32_e32 v40, v40, v42
	v_add_f32_e32 v36, v36, v40
	v_mfma_f32_32x32x16_bf16 v[4:19], v[152:155], v[168:171], v[4:19]
	v_fma_f32 v44, v44, s33, -v107
	v_fma_f32 v45, v45, s33, -v107
	v_fma_f32 v46, v46, s33, -v107
	v_fma_f32 v47, v47, s33, -v107
	v_fma_f32 v48, v48, s33, -v107
	v_fma_f32 v49, v49, s33, -v107
	v_fma_f32 v50, v50, s33, -v107
	v_fma_f32 v51, v51, s33, -v107
	v_exp_f32_e32 v44, v44
	v_exp_f32_e32 v45, v45
	v_exp_f32_e32 v46, v46
	v_exp_f32_e32 v47, v47
	v_exp_f32_e32 v48, v48
	v_exp_f32_e32 v49, v49
	v_exp_f32_e32 v50, v50
	v_exp_f32_e32 v51, v51
	v_cvt_pk_bf16_f32 v176, v44, v45
	v_cvt_pk_bf16_f32 v177, v46, v47
	v_cvt_pk_bf16_f32 v178, v48, v49
	v_cvt_pk_bf16_f32 v179, v50, v51
	v_add_f32_e32 v44, v44, v45
	v_add_f32_e32 v46, v46, v47
	v_add_f32_e32 v48, v48, v49
	v_add_f32_e32 v50, v50, v51
	v_add_f32_e32 v44, v44, v46
	v_add_f32_e32 v48, v48, v50
	v_add_f32_e32 v44, v44, v48
	v_add_f32_e32 v52, v52, v60
	v_add_f32_e32 v36, v36, v44
	v_add_f32_e32 v52, v52, v36
	v_fma_f32 v36, v130, v114, v52
	v_mfma_f32_32x32x16_bf16 v[20:35], v[140:143], v[172:175], v[20:35]
	v_mfma_f32_32x32x16_bf16 v[4:19], v[156:159], v[172:175], v[4:19]
	v_mfma_f32_32x32x16_bf16 v[20:35], v[144:147], v[176:179], v[20:35]
	v_mfma_f32_32x32x16_bf16 v[4:19], v[160:163], v[176:179], v[4:19]
	s_add_i32 s27, s27, 1
	s_add_i32 s26, s26, -1
	s_cmp_lg_u32 s26, -1
	s_cbranch_scc1 .LBB0_373
